# P1 epilogue: non-temporal stores for the sigmoid-gate tiles only (exec-masked dual store)
# baseline (speedup 1.0000x reference)
.LBB0_291:
	s_cmp_eq_u32 s13, 2
	s_cselect_b64 s[72:73], -1, 0
	s_cselect_b64 s[74:75], 0, -1
	s_cmp_gt_i32 s13, 1
	s_mov_b64 s[24:25], -1
	s_cbranch_scc0 .LBB0_293
	v_mul_f32_e32 v156, 0xbfb8aa3b, v129
	v_mul_f32_e32 v150, 0xbfb8aa3b, v126
	v_mul_f32_e32 v151, 0xbfb8aa3b, v122
	v_mul_f32_e32 v152, 0xbfb8aa3b, v127
	v_mul_f32_e32 v153, 0xbfb8aa3b, v123
	v_mul_f32_e32 v154, 0xbfb8aa3b, v128
	v_mul_f32_e32 v155, 0xbfb8aa3b, v124
	v_exp_f32_e32 v156, v156
	v_mul_f32_e32 v157, 0xbfb8aa3b, v125
	v_exp_f32_e32 v150, v150
	v_exp_f32_e32 v151, v151
	v_exp_f32_e32 v152, v152
	v_exp_f32_e32 v153, v153
	v_exp_f32_e32 v154, v154
	v_exp_f32_e32 v155, v155
	v_exp_f32_e32 v158, v157
	v_add_f32_e32 v156, 1.0, v156
	v_add_f32_e32 v150, 1.0, v150
	v_add_f32_e32 v151, 1.0, v151
	v_add_f32_e32 v152, 1.0, v152
	v_add_f32_e32 v153, 1.0, v153
	v_add_f32_e32 v154, 1.0, v154
	v_add_f32_e32 v155, 1.0, v155
	v_rcp_f32_e32 v157, v156
	v_add_f32_e32 v156, 1.0, v158
	v_rcp_f32_e32 v150, v150
	v_rcp_f32_e32 v151, v151
	v_rcp_f32_e32 v152, v152
	v_rcp_f32_e32 v153, v153
	v_rcp_f32_e32 v154, v154
	v_rcp_f32_e32 v155, v155
	v_rcp_f32_e32 v156, v156
	s_cbranch_execnz .LBB0_297
	s_branch .LBB0_294

.LBB0_297:
	s_add_i32 s2, s2, s43
	v_lshl_add_u32 v122, v149, 3, s2
	s_add_i32 s2, s15, s42
	v_add_u32_e32 v126, s2, v148
	v_ashrrev_i32_e32 v124, 31, v126
	v_ashrrev_i32_e32 v123, 31, v122
	v_mul_lo_u32 v127, s22, v124
	v_mul_lo_u32 v128, s23, v126
	v_mad_u64_u32 v[124:125], s[24:25], s22, v126, 0
	v_lshl_add_u64 v[122:123], v[122:123], 1, s[26:27]
	v_add3_u32 v125, v125, v127, v128
	v_lshl_add_u64 v[124:125], v[124:125], 1, v[122:123]
	v_cvt_pk_bf16_f32 v148, v150, v152
	v_cvt_pk_bf16_f32 v149, v154, v157
	v_cvt_pk_bf16_f32 v150, v151, v153
	v_cvt_pk_bf16_f32 v151, v155, v156
	s_cmp_gt_i32 s13, 1
	s_mov_b64 s[24:25], -1
	s_mov_b64 exec, s[74:75]
	global_store_dwordx4 v[124:125], v[148:151], off
	s_mov_b64 exec, s[72:73]
	global_store_dwordx4 v[124:125], v[148:151], off nt
	s_mov_b64 exec, -1
	s_cbranch_scc0 .LBB0_299
	s_nop 0
	v_mul_f32_e32 v151, 0xbfb8aa3b, v121
	v_mul_f32_e32 v127, 0xbfb8aa3b, v118
	v_mul_f32_e32 v128, 0xbfb8aa3b, v114
	v_mul_f32_e32 v129, 0xbfb8aa3b, v119
	v_mul_f32_e32 v148, 0xbfb8aa3b, v115
	v_mul_f32_e32 v149, 0xbfb8aa3b, v120
	v_mul_f32_e32 v150, 0xbfb8aa3b, v116
	v_exp_f32_e32 v151, v151
	v_mul_f32_e32 v152, 0xbfb8aa3b, v117
	v_exp_f32_e32 v127, v127
	v_exp_f32_e32 v128, v128
	v_exp_f32_e32 v129, v129
	v_exp_f32_e32 v148, v148
	v_exp_f32_e32 v149, v149
	v_exp_f32_e32 v150, v150
	v_exp_f32_e32 v153, v152
	v_add_f32_e32 v151, 1.0, v151
	v_add_f32_e32 v127, 1.0, v127
	v_add_f32_e32 v128, 1.0, v128
	v_add_f32_e32 v129, 1.0, v129
	v_add_f32_e32 v148, 1.0, v148
	v_add_f32_e32 v149, 1.0, v149
	v_add_f32_e32 v150, 1.0, v150
	v_rcp_f32_e32 v152, v151
	v_add_f32_e32 v151, 1.0, v153
	v_rcp_f32_e32 v127, v127
	v_rcp_f32_e32 v128, v128
	v_rcp_f32_e32 v129, v129
	v_rcp_f32_e32 v148, v148
	v_rcp_f32_e32 v149, v149
	v_rcp_f32_e32 v150, v150
	v_rcp_f32_e32 v151, v151
	s_mov_b64 s[24:25], 0

.LBB0_303:
	v_cvt_pk_bf16_f32 v114, v127, v129
	v_cvt_pk_bf16_f32 v115, v149, v152
	v_cvt_pk_bf16_f32 v116, v128, v148
	v_cvt_pk_bf16_f32 v117, v150, v151
	s_cmp_gt_i32 s13, 1
	s_mov_b64 s[24:25], -1
	s_mov_b64 exec, s[74:75]
	global_store_dwordx4 v[124:125], v[114:117], off offset:256
	s_mov_b64 exec, s[72:73]
	global_store_dwordx4 v[124:125], v[114:117], off offset:256 nt
	s_mov_b64 exec, -1
	s_cbranch_scc0 .LBB0_305
	v_mul_f32_e32 v120, 0xbfb8aa3b, v113
	v_mul_f32_e32 v114, 0xbfb8aa3b, v110
	v_mul_f32_e32 v115, 0xbfb8aa3b, v106
	v_mul_f32_e32 v116, 0xbfb8aa3b, v111
	v_mul_f32_e32 v117, 0xbfb8aa3b, v107
	v_mul_f32_e32 v118, 0xbfb8aa3b, v112
	v_mul_f32_e32 v119, 0xbfb8aa3b, v108
	v_exp_f32_e32 v120, v120
	v_mul_f32_e32 v121, 0xbfb8aa3b, v109
	v_exp_f32_e32 v114, v114
	v_exp_f32_e32 v115, v115
	v_exp_f32_e32 v116, v116
	v_exp_f32_e32 v117, v117
	v_exp_f32_e32 v118, v118
	v_exp_f32_e32 v119, v119
	v_exp_f32_e32 v124, v121
	v_add_f32_e32 v120, 1.0, v120
	v_add_f32_e32 v114, 1.0, v114
	v_add_f32_e32 v115, 1.0, v115
	v_add_f32_e32 v116, 1.0, v116
	v_add_f32_e32 v117, 1.0, v117
	v_add_f32_e32 v118, 1.0, v118
	v_add_f32_e32 v119, 1.0, v119
	v_rcp_f32_e32 v121, v120
	v_add_f32_e32 v120, 1.0, v124
	v_rcp_f32_e32 v114, v114
	v_rcp_f32_e32 v115, v115
	v_rcp_f32_e32 v116, v116
	v_rcp_f32_e32 v117, v117
	v_rcp_f32_e32 v118, v118
	v_rcp_f32_e32 v119, v119
	v_rcp_f32_e32 v120, v120
	s_mov_b64 s[24:25], 0

.LBB0_309:
	v_add_u32_e32 v106, 16, v126
	v_ashrrev_i32_e32 v107, 31, v106
	v_mul_lo_u32 v108, s22, v107
	v_mul_lo_u32 v109, s23, v106
	v_mad_u64_u32 v[106:107], s[24:25], s22, v106, 0
	v_add3_u32 v107, v107, v108, v109
	v_lshl_add_u64 v[106:107], v[106:107], 1, v[122:123]
	v_cvt_pk_bf16_f32 v108, v114, v116
	v_cvt_pk_bf16_f32 v109, v118, v121
	v_cvt_pk_bf16_f32 v110, v115, v117
	v_cvt_pk_bf16_f32 v111, v119, v120
	s_cmp_gt_i32 s13, 1
	s_mov_b64 s[24:25], -1
	s_mov_b64 exec, s[74:75]
	global_store_dwordx4 v[106:107], v[108:111], off
	s_mov_b64 exec, s[72:73]
	global_store_dwordx4 v[106:107], v[108:111], off nt
	s_mov_b64 exec, -1
	s_cbranch_scc0 .LBB0_311
	v_mul_f32_e32 v114, 0xbfb8aa3b, v105
	v_mul_f32_e32 v108, 0xbfb8aa3b, v102
	v_mul_f32_e32 v109, 0xbfb8aa3b, v98
	v_mul_f32_e32 v110, 0xbfb8aa3b, v103
	v_mul_f32_e32 v111, 0xbfb8aa3b, v99
	v_mul_f32_e32 v112, 0xbfb8aa3b, v104
	v_mul_f32_e32 v113, 0xbfb8aa3b, v100
	v_exp_f32_e32 v114, v114
	v_mul_f32_e32 v115, 0xbfb8aa3b, v101
	v_exp_f32_e32 v108, v108
	v_exp_f32_e32 v109, v109
	v_exp_f32_e32 v110, v110
	v_exp_f32_e32 v111, v111
	v_exp_f32_e32 v112, v112
	v_exp_f32_e32 v113, v113
	v_exp_f32_e32 v116, v115
	v_add_f32_e32 v114, 1.0, v114
	v_add_f32_e32 v108, 1.0, v108
	v_add_f32_e32 v109, 1.0, v109
	v_add_f32_e32 v110, 1.0, v110
	v_add_f32_e32 v111, 1.0, v111
	v_add_f32_e32 v112, 1.0, v112
	v_add_f32_e32 v113, 1.0, v113
	v_rcp_f32_e32 v115, v114
	v_add_f32_e32 v114, 1.0, v116
	v_rcp_f32_e32 v108, v108
	v_rcp_f32_e32 v109, v109
	v_rcp_f32_e32 v110, v110
	v_rcp_f32_e32 v111, v111
	v_rcp_f32_e32 v112, v112
	v_rcp_f32_e32 v113, v113
	v_rcp_f32_e32 v114, v114
	s_mov_b64 s[24:25], 0

.LBB0_315:
	v_cvt_pk_bf16_f32 v98, v108, v110
	v_cvt_pk_bf16_f32 v99, v112, v115
	v_cvt_pk_bf16_f32 v100, v109, v111
	v_cvt_pk_bf16_f32 v101, v113, v114
	s_cmp_gt_i32 s13, 1
	s_mov_b64 s[24:25], -1
	s_mov_b64 exec, s[74:75]
	global_store_dwordx4 v[106:107], v[98:101], off offset:256
	s_mov_b64 exec, s[72:73]
	global_store_dwordx4 v[106:107], v[98:101], off offset:256 nt
	s_mov_b64 exec, -1
	s_cbranch_scc0 .LBB0_317
	v_mul_f32_e32 v104, 0xbfb8aa3b, v97
	v_mul_f32_e32 v98, 0xbfb8aa3b, v94
	v_mul_f32_e32 v99, 0xbfb8aa3b, v90
	v_mul_f32_e32 v100, 0xbfb8aa3b, v95
	v_mul_f32_e32 v101, 0xbfb8aa3b, v91
	v_mul_f32_e32 v102, 0xbfb8aa3b, v96
	v_mul_f32_e32 v103, 0xbfb8aa3b, v92
	v_exp_f32_e32 v104, v104
	v_mul_f32_e32 v105, 0xbfb8aa3b, v93
	v_exp_f32_e32 v98, v98
	v_exp_f32_e32 v99, v99
	v_exp_f32_e32 v100, v100
	v_exp_f32_e32 v101, v101
	v_exp_f32_e32 v102, v102
	v_exp_f32_e32 v103, v103
	v_exp_f32_e32 v106, v105
	v_add_f32_e32 v104, 1.0, v104
	v_add_f32_e32 v98, 1.0, v98
	v_add_f32_e32 v99, 1.0, v99
	v_add_f32_e32 v100, 1.0, v100
	v_add_f32_e32 v101, 1.0, v101
	v_add_f32_e32 v102, 1.0, v102
	v_add_f32_e32 v103, 1.0, v103
	v_rcp_f32_e32 v105, v104
	v_add_f32_e32 v104, 1.0, v106
	v_rcp_f32_e32 v98, v98
	v_rcp_f32_e32 v99, v99
	v_rcp_f32_e32 v100, v100
	v_rcp_f32_e32 v101, v101
	v_rcp_f32_e32 v102, v102
	v_rcp_f32_e32 v103, v103
	v_rcp_f32_e32 v104, v104
	s_mov_b64 s[24:25], 0

.LBB0_321:
	v_add_u32_e32 v90, 32, v126
	v_ashrrev_i32_e32 v91, 31, v90
	v_mul_lo_u32 v92, s22, v91
	v_mul_lo_u32 v93, s23, v90
	v_mad_u64_u32 v[90:91], s[24:25], s22, v90, 0
	v_add3_u32 v91, v91, v92, v93
	v_lshl_add_u64 v[90:91], v[90:91], 1, v[122:123]
	v_cvt_pk_bf16_f32 v92, v98, v100
	v_cvt_pk_bf16_f32 v93, v102, v105
	v_cvt_pk_bf16_f32 v94, v99, v101
	v_cvt_pk_bf16_f32 v95, v103, v104
	s_cmp_gt_i32 s13, 1
	s_mov_b64 s[24:25], -1
	s_mov_b64 exec, s[74:75]
	global_store_dwordx4 v[90:91], v[92:95], off
	s_mov_b64 exec, s[72:73]
	global_store_dwordx4 v[90:91], v[92:95], off nt
	s_mov_b64 exec, -1
	s_cbranch_scc0 .LBB0_323
	v_mul_f32_e32 v98, 0xbfb8aa3b, v89
	v_mul_f32_e32 v92, 0xbfb8aa3b, v86
	v_mul_f32_e32 v93, 0xbfb8aa3b, v82
	v_mul_f32_e32 v94, 0xbfb8aa3b, v87
	v_mul_f32_e32 v95, 0xbfb8aa3b, v83
	v_mul_f32_e32 v96, 0xbfb8aa3b, v88
	v_mul_f32_e32 v97, 0xbfb8aa3b, v84
	v_exp_f32_e32 v98, v98
	v_mul_f32_e32 v99, 0xbfb8aa3b, v85
	v_exp_f32_e32 v92, v92
	v_exp_f32_e32 v93, v93
	v_exp_f32_e32 v94, v94
	v_exp_f32_e32 v95, v95
	v_exp_f32_e32 v96, v96
	v_exp_f32_e32 v97, v97
	v_exp_f32_e32 v100, v99
	v_add_f32_e32 v98, 1.0, v98
	v_add_f32_e32 v92, 1.0, v92
	v_add_f32_e32 v93, 1.0, v93
	v_add_f32_e32 v94, 1.0, v94
	v_add_f32_e32 v95, 1.0, v95
	v_add_f32_e32 v96, 1.0, v96
	v_add_f32_e32 v97, 1.0, v97
	v_rcp_f32_e32 v99, v98
	v_add_f32_e32 v98, 1.0, v100
	v_rcp_f32_e32 v92, v92
	v_rcp_f32_e32 v93, v93
	v_rcp_f32_e32 v94, v94
	v_rcp_f32_e32 v95, v95
	v_rcp_f32_e32 v96, v96
	v_rcp_f32_e32 v97, v97
	v_rcp_f32_e32 v98, v98
	s_mov_b64 s[24:25], 0

.LBB0_327:
	v_cvt_pk_bf16_f32 v82, v92, v94
	v_cvt_pk_bf16_f32 v83, v96, v99
	v_cvt_pk_bf16_f32 v84, v93, v95
	v_cvt_pk_bf16_f32 v85, v97, v98
	s_cmp_gt_i32 s13, 1
	s_mov_b64 s[24:25], -1
	s_mov_b64 exec, s[74:75]
	global_store_dwordx4 v[90:91], v[82:85], off offset:256
	s_mov_b64 exec, s[72:73]
	global_store_dwordx4 v[90:91], v[82:85], off offset:256 nt
	s_mov_b64 exec, -1
	s_cbranch_scc0 .LBB0_329
	v_mul_f32_e32 v88, 0xbfb8aa3b, v81
	v_mul_f32_e32 v82, 0xbfb8aa3b, v78
	v_mul_f32_e32 v83, 0xbfb8aa3b, v74
	v_mul_f32_e32 v84, 0xbfb8aa3b, v79
	v_mul_f32_e32 v85, 0xbfb8aa3b, v75
	v_mul_f32_e32 v86, 0xbfb8aa3b, v80
	v_mul_f32_e32 v87, 0xbfb8aa3b, v76
	v_exp_f32_e32 v88, v88
	v_mul_f32_e32 v89, 0xbfb8aa3b, v77
	v_exp_f32_e32 v82, v82
	v_exp_f32_e32 v83, v83
	v_exp_f32_e32 v84, v84
	v_exp_f32_e32 v85, v85
	v_exp_f32_e32 v86, v86
	v_exp_f32_e32 v87, v87
	v_exp_f32_e32 v90, v89
	v_add_f32_e32 v88, 1.0, v88
	v_add_f32_e32 v82, 1.0, v82
	v_add_f32_e32 v83, 1.0, v83
	v_add_f32_e32 v84, 1.0, v84
	v_add_f32_e32 v85, 1.0, v85
	v_add_f32_e32 v86, 1.0, v86
	v_add_f32_e32 v87, 1.0, v87
	v_rcp_f32_e32 v89, v88
	v_add_f32_e32 v88, 1.0, v90
	v_rcp_f32_e32 v82, v82
	v_rcp_f32_e32 v83, v83
	v_rcp_f32_e32 v84, v84
	v_rcp_f32_e32 v85, v85
	v_rcp_f32_e32 v86, v86
	v_rcp_f32_e32 v87, v87
	v_rcp_f32_e32 v88, v88
	s_mov_b64 s[24:25], 0

.LBB0_333:
	v_add_u32_e32 v74, 48, v126
	v_ashrrev_i32_e32 v75, 31, v74
	v_mul_lo_u32 v76, s22, v75
	v_mul_lo_u32 v77, s23, v74
	v_mad_u64_u32 v[74:75], s[24:25], s22, v74, 0
	v_add3_u32 v75, v75, v76, v77
	v_lshl_add_u64 v[74:75], v[74:75], 1, v[122:123]
	v_cvt_pk_bf16_f32 v76, v82, v84
	v_cvt_pk_bf16_f32 v77, v86, v89
	v_cvt_pk_bf16_f32 v78, v83, v85
	v_cvt_pk_bf16_f32 v79, v87, v88
	s_cmp_gt_i32 s13, 1
	s_mov_b64 s[24:25], -1
	s_mov_b64 exec, s[74:75]
	global_store_dwordx4 v[74:75], v[76:79], off
	s_mov_b64 exec, s[72:73]
	global_store_dwordx4 v[74:75], v[76:79], off nt
	s_mov_b64 exec, -1
	s_cbranch_scc0 .LBB0_335
	v_mul_f32_e32 v82, 0xbfb8aa3b, v73
	v_mul_f32_e32 v76, 0xbfb8aa3b, v70
	v_mul_f32_e32 v77, 0xbfb8aa3b, v66
	v_mul_f32_e32 v78, 0xbfb8aa3b, v71
	v_mul_f32_e32 v79, 0xbfb8aa3b, v67
	v_mul_f32_e32 v80, 0xbfb8aa3b, v72
	v_mul_f32_e32 v81, 0xbfb8aa3b, v68
	v_exp_f32_e32 v82, v82
	v_mul_f32_e32 v83, 0xbfb8aa3b, v69
	v_exp_f32_e32 v76, v76
	v_exp_f32_e32 v77, v77
	v_exp_f32_e32 v78, v78
	v_exp_f32_e32 v79, v79
	v_exp_f32_e32 v80, v80
	v_exp_f32_e32 v81, v81
	v_exp_f32_e32 v84, v83
	v_add_f32_e32 v82, 1.0, v82
	v_add_f32_e32 v76, 1.0, v76
	v_add_f32_e32 v77, 1.0, v77
	v_add_f32_e32 v78, 1.0, v78
	v_add_f32_e32 v79, 1.0, v79
	v_add_f32_e32 v80, 1.0, v80
	v_add_f32_e32 v81, 1.0, v81
	v_rcp_f32_e32 v83, v82
	v_add_f32_e32 v82, 1.0, v84
	v_rcp_f32_e32 v76, v76
	v_rcp_f32_e32 v77, v77
	v_rcp_f32_e32 v78, v78
	v_rcp_f32_e32 v79, v79
	v_rcp_f32_e32 v80, v80
	v_rcp_f32_e32 v81, v81
	v_rcp_f32_e32 v82, v82
	s_mov_b64 s[24:25], 0

.LBB0_339:
	v_cvt_pk_bf16_f32 v66, v76, v78
	v_cvt_pk_bf16_f32 v67, v80, v83
	v_cvt_pk_bf16_f32 v68, v77, v79
	v_cvt_pk_bf16_f32 v69, v81, v82
	s_cmp_gt_i32 s13, 1
	s_mov_b64 s[24:25], -1
	s_mov_b64 exec, s[74:75]
	global_store_dwordx4 v[74:75], v[66:69], off offset:256
	s_mov_b64 exec, s[72:73]
	global_store_dwordx4 v[74:75], v[66:69], off offset:256 nt
	s_mov_b64 exec, -1
	s_cbranch_scc0 .LBB0_341
	v_mul_f32_e32 v72, 0xbfb8aa3b, v65
	v_mul_f32_e32 v66, 0xbfb8aa3b, v62
	v_mul_f32_e32 v67, 0xbfb8aa3b, v58
	v_mul_f32_e32 v68, 0xbfb8aa3b, v63
	v_mul_f32_e32 v69, 0xbfb8aa3b, v59
	v_mul_f32_e32 v70, 0xbfb8aa3b, v64
	v_mul_f32_e32 v71, 0xbfb8aa3b, v60
	v_exp_f32_e32 v72, v72
	v_mul_f32_e32 v73, 0xbfb8aa3b, v61
	v_exp_f32_e32 v66, v66
	v_exp_f32_e32 v67, v67
	v_exp_f32_e32 v68, v68
	v_exp_f32_e32 v69, v69
	v_exp_f32_e32 v70, v70
	v_exp_f32_e32 v71, v71
	v_exp_f32_e32 v74, v73
	v_add_f32_e32 v72, 1.0, v72
	v_add_f32_e32 v66, 1.0, v66
	v_add_f32_e32 v67, 1.0, v67
	v_add_f32_e32 v68, 1.0, v68
	v_add_f32_e32 v69, 1.0, v69
	v_add_f32_e32 v70, 1.0, v70
	v_add_f32_e32 v71, 1.0, v71
	v_rcp_f32_e32 v73, v72
	v_add_f32_e32 v72, 1.0, v74
	v_rcp_f32_e32 v66, v66
	v_rcp_f32_e32 v67, v67
	v_rcp_f32_e32 v68, v68
	v_rcp_f32_e32 v69, v69
	v_rcp_f32_e32 v70, v70
	v_rcp_f32_e32 v71, v71
	v_rcp_f32_e32 v72, v72
	s_mov_b64 s[24:25], 0

.LBB0_345:
	v_add_u32_e32 v58, 0x80, v126
	v_ashrrev_i32_e32 v59, 31, v58
	v_mul_lo_u32 v60, s22, v59
	v_mul_lo_u32 v61, s23, v58
	v_mad_u64_u32 v[58:59], s[24:25], s22, v58, 0
	v_add3_u32 v59, v59, v60, v61
	v_lshl_add_u64 v[58:59], v[58:59], 1, v[122:123]
	v_cvt_pk_bf16_f32 v60, v66, v68
	v_cvt_pk_bf16_f32 v61, v70, v73
	v_cvt_pk_bf16_f32 v62, v67, v69
	v_cvt_pk_bf16_f32 v63, v71, v72
	s_cmp_gt_i32 s13, 1
	s_mov_b64 s[24:25], -1
	s_mov_b64 exec, s[74:75]
	global_store_dwordx4 v[58:59], v[60:63], off
	s_mov_b64 exec, s[72:73]
	global_store_dwordx4 v[58:59], v[60:63], off nt
	s_mov_b64 exec, -1
	s_cbranch_scc0 .LBB0_347
	v_mul_f32_e32 v66, 0xbfb8aa3b, v57
	v_mul_f32_e32 v60, 0xbfb8aa3b, v54
	v_mul_f32_e32 v61, 0xbfb8aa3b, v50
	v_mul_f32_e32 v62, 0xbfb8aa3b, v55
	v_mul_f32_e32 v63, 0xbfb8aa3b, v51
	v_mul_f32_e32 v64, 0xbfb8aa3b, v56
	v_mul_f32_e32 v65, 0xbfb8aa3b, v52
	v_exp_f32_e32 v66, v66
	v_mul_f32_e32 v67, 0xbfb8aa3b, v53
	v_exp_f32_e32 v60, v60
	v_exp_f32_e32 v61, v61
	v_exp_f32_e32 v62, v62
	v_exp_f32_e32 v63, v63
	v_exp_f32_e32 v64, v64
	v_exp_f32_e32 v65, v65
	v_exp_f32_e32 v68, v67
	v_add_f32_e32 v66, 1.0, v66
	v_add_f32_e32 v60, 1.0, v60
	v_add_f32_e32 v61, 1.0, v61
	v_add_f32_e32 v62, 1.0, v62
	v_add_f32_e32 v63, 1.0, v63
	v_add_f32_e32 v64, 1.0, v64
	v_add_f32_e32 v65, 1.0, v65
	v_rcp_f32_e32 v67, v66
	v_add_f32_e32 v66, 1.0, v68
	v_rcp_f32_e32 v60, v60
	v_rcp_f32_e32 v61, v61
	v_rcp_f32_e32 v62, v62
	v_rcp_f32_e32 v63, v63
	v_rcp_f32_e32 v64, v64
	v_rcp_f32_e32 v65, v65
	v_rcp_f32_e32 v66, v66
	s_mov_b64 s[24:25], 0

.LBB0_351:
	v_cvt_pk_bf16_f32 v50, v60, v62
	v_cvt_pk_bf16_f32 v51, v64, v67
	v_cvt_pk_bf16_f32 v52, v61, v63
	v_cvt_pk_bf16_f32 v53, v65, v66
	s_cmp_gt_i32 s13, 1
	s_mov_b64 s[24:25], -1
	s_mov_b64 exec, s[74:75]
	global_store_dwordx4 v[58:59], v[50:53], off offset:256
	s_mov_b64 exec, s[72:73]
	global_store_dwordx4 v[58:59], v[50:53], off offset:256 nt
	s_mov_b64 exec, -1
	s_cbranch_scc0 .LBB0_353
	v_mul_f32_e32 v56, 0xbfb8aa3b, v49
	v_mul_f32_e32 v50, 0xbfb8aa3b, v46
	v_mul_f32_e32 v51, 0xbfb8aa3b, v42
	v_mul_f32_e32 v52, 0xbfb8aa3b, v47
	v_mul_f32_e32 v53, 0xbfb8aa3b, v43
	v_mul_f32_e32 v54, 0xbfb8aa3b, v48
	v_mul_f32_e32 v55, 0xbfb8aa3b, v44
	v_exp_f32_e32 v56, v56
	v_mul_f32_e32 v57, 0xbfb8aa3b, v45
	v_exp_f32_e32 v50, v50
	v_exp_f32_e32 v51, v51
	v_exp_f32_e32 v52, v52
	v_exp_f32_e32 v53, v53
	v_exp_f32_e32 v54, v54
	v_exp_f32_e32 v55, v55
	v_exp_f32_e32 v58, v57
	v_add_f32_e32 v56, 1.0, v56
	v_add_f32_e32 v50, 1.0, v50
	v_add_f32_e32 v51, 1.0, v51
	v_add_f32_e32 v52, 1.0, v52
	v_add_f32_e32 v53, 1.0, v53
	v_add_f32_e32 v54, 1.0, v54
	v_add_f32_e32 v55, 1.0, v55
	v_rcp_f32_e32 v57, v56
	v_add_f32_e32 v56, 1.0, v58
	v_rcp_f32_e32 v50, v50
	v_rcp_f32_e32 v51, v51
	v_rcp_f32_e32 v52, v52
	v_rcp_f32_e32 v53, v53
	v_rcp_f32_e32 v54, v54
	v_rcp_f32_e32 v55, v55
	v_rcp_f32_e32 v56, v56
	s_mov_b64 s[24:25], 0

.LBB0_357:
	v_add_u32_e32 v42, 0x90, v126
	v_ashrrev_i32_e32 v43, 31, v42
	v_mul_lo_u32 v44, s22, v43
	v_mul_lo_u32 v45, s23, v42
	v_mad_u64_u32 v[42:43], s[24:25], s22, v42, 0
	v_add3_u32 v43, v43, v44, v45
	v_lshl_add_u64 v[42:43], v[42:43], 1, v[122:123]
	v_cvt_pk_bf16_f32 v44, v50, v52
	v_cvt_pk_bf16_f32 v45, v54, v57
	v_cvt_pk_bf16_f32 v46, v51, v53
	v_cvt_pk_bf16_f32 v47, v55, v56
	s_cmp_gt_i32 s13, 1
	s_mov_b64 s[24:25], -1
	s_mov_b64 exec, s[74:75]
	global_store_dwordx4 v[42:43], v[44:47], off
	s_mov_b64 exec, s[72:73]
	global_store_dwordx4 v[42:43], v[44:47], off nt
	s_mov_b64 exec, -1
	s_cbranch_scc0 .LBB0_359
	v_mul_f32_e32 v50, 0xbfb8aa3b, v41
	v_mul_f32_e32 v44, 0xbfb8aa3b, v38
	v_mul_f32_e32 v45, 0xbfb8aa3b, v34
	v_mul_f32_e32 v46, 0xbfb8aa3b, v39
	v_mul_f32_e32 v47, 0xbfb8aa3b, v35
	v_mul_f32_e32 v48, 0xbfb8aa3b, v40
	v_mul_f32_e32 v49, 0xbfb8aa3b, v36
	v_exp_f32_e32 v50, v50
	v_mul_f32_e32 v51, 0xbfb8aa3b, v37
	v_exp_f32_e32 v44, v44
	v_exp_f32_e32 v45, v45
	v_exp_f32_e32 v46, v46
	v_exp_f32_e32 v47, v47
	v_exp_f32_e32 v48, v48
	v_exp_f32_e32 v49, v49
	v_exp_f32_e32 v52, v51
	v_add_f32_e32 v50, 1.0, v50
	v_add_f32_e32 v44, 1.0, v44
	v_add_f32_e32 v45, 1.0, v45
	v_add_f32_e32 v46, 1.0, v46
	v_add_f32_e32 v47, 1.0, v47
	v_add_f32_e32 v48, 1.0, v48
	v_add_f32_e32 v49, 1.0, v49
	v_rcp_f32_e32 v51, v50
	v_add_f32_e32 v50, 1.0, v52
	v_rcp_f32_e32 v44, v44
	v_rcp_f32_e32 v45, v45
	v_rcp_f32_e32 v46, v46
	v_rcp_f32_e32 v47, v47
	v_rcp_f32_e32 v48, v48
	v_rcp_f32_e32 v49, v49
	v_rcp_f32_e32 v50, v50
	s_mov_b64 s[24:25], 0

.LBB0_363:
	v_cvt_pk_bf16_f32 v34, v44, v46
	v_cvt_pk_bf16_f32 v35, v48, v51
	v_cvt_pk_bf16_f32 v36, v45, v47
	v_cvt_pk_bf16_f32 v37, v49, v50
	s_cmp_gt_i32 s13, 1
	s_mov_b64 s[24:25], -1
	s_mov_b64 exec, s[74:75]
	global_store_dwordx4 v[42:43], v[34:37], off offset:256
	s_mov_b64 exec, s[72:73]
	global_store_dwordx4 v[42:43], v[34:37], off offset:256 nt
	s_mov_b64 exec, -1
	s_cbranch_scc0 .LBB0_365
	v_mul_f32_e32 v40, 0xbfb8aa3b, v33
	v_mul_f32_e32 v34, 0xbfb8aa3b, v30
	v_mul_f32_e32 v35, 0xbfb8aa3b, v26
	v_mul_f32_e32 v36, 0xbfb8aa3b, v31
	v_mul_f32_e32 v37, 0xbfb8aa3b, v27
	v_mul_f32_e32 v38, 0xbfb8aa3b, v32
	v_mul_f32_e32 v39, 0xbfb8aa3b, v28
	v_exp_f32_e32 v40, v40
	v_mul_f32_e32 v41, 0xbfb8aa3b, v29
	v_exp_f32_e32 v34, v34
	v_exp_f32_e32 v35, v35
	v_exp_f32_e32 v36, v36
	v_exp_f32_e32 v37, v37
	v_exp_f32_e32 v38, v38
	v_exp_f32_e32 v39, v39
	v_exp_f32_e32 v42, v41
	v_add_f32_e32 v40, 1.0, v40
	v_add_f32_e32 v34, 1.0, v34
	v_add_f32_e32 v35, 1.0, v35
	v_add_f32_e32 v36, 1.0, v36
	v_add_f32_e32 v37, 1.0, v37
	v_add_f32_e32 v38, 1.0, v38
	v_add_f32_e32 v39, 1.0, v39
	v_rcp_f32_e32 v41, v40
	v_add_f32_e32 v40, 1.0, v42
	v_rcp_f32_e32 v34, v34
	v_rcp_f32_e32 v35, v35
	v_rcp_f32_e32 v36, v36
	v_rcp_f32_e32 v37, v37
	v_rcp_f32_e32 v38, v38
	v_rcp_f32_e32 v39, v39
	v_rcp_f32_e32 v40, v40
	s_mov_b64 s[24:25], 0

.LBB0_369:
	v_add_u32_e32 v26, 0xa0, v126
	v_ashrrev_i32_e32 v27, 31, v26
	v_mul_lo_u32 v28, s22, v27
	v_mul_lo_u32 v29, s23, v26
	v_mad_u64_u32 v[26:27], s[24:25], s22, v26, 0
	v_add3_u32 v27, v27, v28, v29
	v_lshl_add_u64 v[26:27], v[26:27], 1, v[122:123]
	v_cvt_pk_bf16_f32 v28, v34, v36
	v_cvt_pk_bf16_f32 v29, v38, v41
	v_cvt_pk_bf16_f32 v30, v35, v37
	v_cvt_pk_bf16_f32 v31, v39, v40
	s_cmp_gt_i32 s13, 1
	s_mov_b64 s[24:25], -1
	s_mov_b64 exec, s[74:75]
	global_store_dwordx4 v[26:27], v[28:31], off
	s_mov_b64 exec, s[72:73]
	global_store_dwordx4 v[26:27], v[28:31], off nt
	s_mov_b64 exec, -1
	s_cbranch_scc0 .LBB0_371
	v_mul_f32_e32 v34, 0xbfb8aa3b, v25
	v_mul_f32_e32 v28, 0xbfb8aa3b, v22
	v_mul_f32_e32 v29, 0xbfb8aa3b, v18
	v_mul_f32_e32 v30, 0xbfb8aa3b, v23
	v_mul_f32_e32 v31, 0xbfb8aa3b, v19
	v_mul_f32_e32 v32, 0xbfb8aa3b, v24
	v_mul_f32_e32 v33, 0xbfb8aa3b, v20
	v_exp_f32_e32 v34, v34
	v_mul_f32_e32 v35, 0xbfb8aa3b, v21
	v_exp_f32_e32 v28, v28
	v_exp_f32_e32 v29, v29
	v_exp_f32_e32 v30, v30
	v_exp_f32_e32 v31, v31
	v_exp_f32_e32 v32, v32
	v_exp_f32_e32 v33, v33
	v_exp_f32_e32 v36, v35
	v_add_f32_e32 v34, 1.0, v34
	v_add_f32_e32 v28, 1.0, v28
	v_add_f32_e32 v29, 1.0, v29
	v_add_f32_e32 v30, 1.0, v30
	v_add_f32_e32 v31, 1.0, v31
	v_add_f32_e32 v32, 1.0, v32
	v_add_f32_e32 v33, 1.0, v33
	v_rcp_f32_e32 v35, v34
	v_add_f32_e32 v34, 1.0, v36
	v_rcp_f32_e32 v28, v28
	v_rcp_f32_e32 v29, v29
	v_rcp_f32_e32 v30, v30
	v_rcp_f32_e32 v31, v31
	v_rcp_f32_e32 v32, v32
	v_rcp_f32_e32 v33, v33
	v_rcp_f32_e32 v34, v34
	s_mov_b64 s[24:25], 0

.LBB0_375:
	v_cvt_pk_bf16_f32 v18, v28, v30
	v_cvt_pk_bf16_f32 v19, v32, v35
	v_cvt_pk_bf16_f32 v20, v29, v31
	v_cvt_pk_bf16_f32 v21, v33, v34
	s_cmp_gt_i32 s13, 1
	s_mov_b64 s[24:25], -1
	s_mov_b64 exec, s[74:75]
	global_store_dwordx4 v[26:27], v[18:21], off offset:256
	s_mov_b64 exec, s[72:73]
	global_store_dwordx4 v[26:27], v[18:21], off offset:256 nt
	s_mov_b64 exec, -1
	s_cbranch_scc0 .LBB0_377
	v_mul_f32_e32 v24, 0xbfb8aa3b, v17
	v_mul_f32_e32 v18, 0xbfb8aa3b, v14
	v_mul_f32_e32 v19, 0xbfb8aa3b, v10
	v_mul_f32_e32 v20, 0xbfb8aa3b, v15
	v_mul_f32_e32 v21, 0xbfb8aa3b, v11
	v_mul_f32_e32 v22, 0xbfb8aa3b, v16
	v_mul_f32_e32 v23, 0xbfb8aa3b, v12
	v_exp_f32_e32 v24, v24
	v_mul_f32_e32 v25, 0xbfb8aa3b, v13
	v_exp_f32_e32 v18, v18
	v_exp_f32_e32 v19, v19
	v_exp_f32_e32 v20, v20
	v_exp_f32_e32 v21, v21
	v_exp_f32_e32 v22, v22
	v_exp_f32_e32 v23, v23
	v_exp_f32_e32 v26, v25
	v_add_f32_e32 v24, 1.0, v24
	v_add_f32_e32 v18, 1.0, v18
	v_add_f32_e32 v19, 1.0, v19
	v_add_f32_e32 v20, 1.0, v20
	v_add_f32_e32 v21, 1.0, v21
	v_add_f32_e32 v22, 1.0, v22
	v_add_f32_e32 v23, 1.0, v23
	v_rcp_f32_e32 v25, v24
	v_add_f32_e32 v24, 1.0, v26
	v_rcp_f32_e32 v18, v18
	v_rcp_f32_e32 v19, v19
	v_rcp_f32_e32 v20, v20
	v_rcp_f32_e32 v21, v21
	v_rcp_f32_e32 v22, v22
	v_rcp_f32_e32 v23, v23
	v_rcp_f32_e32 v24, v24
	s_mov_b64 s[24:25], 0

.LBB0_381:
	v_add_u32_e32 v10, 0xb0, v126
	v_ashrrev_i32_e32 v11, 31, v10
	v_mul_lo_u32 v12, s22, v11
	v_mul_lo_u32 v13, s23, v10
	v_mad_u64_u32 v[10:11], s[22:23], s22, v10, 0
	v_add3_u32 v11, v11, v12, v13
	v_lshl_add_u64 v[10:11], v[10:11], 1, v[122:123]
	v_cvt_pk_bf16_f32 v12, v18, v20
	v_cvt_pk_bf16_f32 v13, v22, v25
	v_cvt_pk_bf16_f32 v14, v19, v21
	v_cvt_pk_bf16_f32 v15, v23, v24
	s_cmp_gt_i32 s13, 1
	s_mov_b64 s[22:23], -1
	s_mov_b64 exec, s[74:75]
	global_store_dwordx4 v[10:11], v[12:15], off
	s_mov_b64 exec, s[72:73]
	global_store_dwordx4 v[10:11], v[12:15], off nt
	s_mov_b64 exec, -1
	s_cbranch_scc0 .LBB0_383
	v_mul_f32_e32 v18, 0xbfb8aa3b, v9
	v_mul_f32_e32 v12, 0xbfb8aa3b, v6
	v_mul_f32_e32 v13, 0xbfb8aa3b, v2
	v_mul_f32_e32 v14, 0xbfb8aa3b, v7
	v_mul_f32_e32 v15, 0xbfb8aa3b, v3
	v_mul_f32_e32 v16, 0xbfb8aa3b, v8
	v_mul_f32_e32 v17, 0xbfb8aa3b, v4
	v_exp_f32_e32 v18, v18
	v_mul_f32_e32 v19, 0xbfb8aa3b, v5
	v_exp_f32_e32 v12, v12
	v_exp_f32_e32 v13, v13
	v_exp_f32_e32 v14, v14
	v_exp_f32_e32 v15, v15
	v_exp_f32_e32 v16, v16
	v_exp_f32_e32 v17, v17
	v_exp_f32_e32 v20, v19
	v_add_f32_e32 v18, 1.0, v18
	v_add_f32_e32 v12, 1.0, v12
	v_add_f32_e32 v13, 1.0, v13
	v_add_f32_e32 v14, 1.0, v14
	v_add_f32_e32 v15, 1.0, v15
	v_add_f32_e32 v16, 1.0, v16
	v_add_f32_e32 v17, 1.0, v17
	v_rcp_f32_e32 v19, v18
	v_add_f32_e32 v18, 1.0, v20
	v_rcp_f32_e32 v12, v12
	v_rcp_f32_e32 v13, v13
	v_rcp_f32_e32 v14, v14
	v_rcp_f32_e32 v15, v15
	v_rcp_f32_e32 v16, v16
	v_rcp_f32_e32 v17, v17
	v_rcp_f32_e32 v18, v18
	s_mov_b64 s[22:23], 0

.LBB0_387:
	s_andn2_b64 vcc, exec, s[20:21]
	s_mov_b64 s[20:21], -1
	v_cvt_pk_bf16_f32 v2, v12, v14
	v_cvt_pk_bf16_f32 v3, v16, v19
	v_cvt_pk_bf16_f32 v4, v13, v15
	v_cvt_pk_bf16_f32 v5, v17, v18
	s_mov_b64 exec, s[74:75]
	global_store_dwordx4 v[10:11], v[2:5], off offset:256
	s_mov_b64 exec, s[72:73]
	global_store_dwordx4 v[10:11], v[2:5], off offset:256 nt
	s_mov_b64 exec, -1
	s_cbranch_vccnz .LBB0_265
	s_andn2_b64 vcc, exec, s[6:7]
	s_cbranch_vccnz .LBB0_264
	s_barrier
	s_branch .LBB0_264
